# pooling phase rewritten by hand (all window rows loaded before the adds); first grid sync uses the counter barrier
# speedup vs baseline: 1.0356x; 1.0180x over previous
; DI int ltid() { int t = threadIdx.x; asm volatile("" : "+v"(t)); return t; }
; DI int lbid() { int t = blockIdx.x; asm volatile("" : "+s"(t)); return t; }
; DI float bflo(unsigned u) { return __uint_as_float(u << 16); }
; DI float bfhi(unsigned u) { return __uint_as_float(u & 0xffff0000u); }
; DI void phase_od_pool(const Params& P) {
;     char* ws = P.ws; const bf16_t* U = (const bf16_t*)(ws + OFF_HID + HOFF_U); bf16_t* PL = (bf16_t*)(ws + OFF_HID + HOFF_PL);
;     const size_t gtid = (size_t)lbid() * NTHR + ltid(), gstride = (size_t)gridDim.x * NTHR;
;     for (size_t i = gtid; i < (size_t)RT * 64; i += gstride) {
;         const int row = (int)(i >> 6), c = (int)(i & 63) * 8, grp = c >> 7;
;         const int w = 2 << grp, left = w >> 1, right = w - 1 - left;
;         int base, n, t;
;         if (row < RL) { base = row & ~8191; n = SEQ; t = row & 8191; } else { const int rc = row - RL; base = RL + (rc & ~255); n = CTX; t = rc & 255; }
;         const int lo = max(t - left, 0), hi = min(t + right + 1, n);
;         float acc[8] = {0.f, 0.f, 0.f, 0.f, 0.f, 0.f, 0.f, 0.f};
; #pragma unroll 4
;         for (int tt = lo; tt < hi; ++tt) {
;             const u32x4 v = *(const u32x4*)(U + (size_t)(base + tt) * 512 + c);
;             acc[0] += bflo(v.x); acc[1] += bfhi(v.x); acc[2] += bflo(v.y); acc[3] += bfhi(v.y); acc[4] += bflo(v.z); acc[5] += bfhi(v.z); acc[6] += bflo(v.w); acc[7] += bfhi(v.w);
;         }
;         const float ic = 1.f / (float)(hi - lo);
.Lmy_pool_entry:
	v_readlane_b32 s0, v253, 0
	v_readlane_b32 s2, v253, 9
	v_readlane_b32 s3, v253, 10
	v_lshrrev_b32_e32 v85, 6, v194
	s_nop 3
	s_load_dword s9, s[2:3], 0x0
	v_readfirstlane_b32 s1, v85
	v_writelane_b32 v254, s0, 53
	v_lshlrev_b32_e32 v80, 4, v197
	v_lshrrev_b32_e32 v86, 4, v197
	v_lshlrev_b32_e64 v81, v86, 1
	v_add_u32_e32 v82, -1, v81
	s_waitcnt lgkmcnt(0)
	s_lshl_b32 s0, s0, 3
	s_add_u32 s8, s0, s1
	s_lshl_b32 s9, s9, 3
	s_cmp_ge_u32 s8, 0x8400
	s_cbranch_scc1 .Lmy_pool_done
.Lmy_pool_loop:
	s_cmp_ge_u32 s8, 0x8000
	s_movk_i32 s2, 0x1fff
	s_cselect_b32 s2, 0xff, s2
	s_and_b32 s10, s8, s2
	s_add_u32 s11, s2, 1
	s_sub_i32 s12, 0, s10
	s_max_i32 s12, s12, -8
	s_sub_i32 s4, s2, s10
	s_min_i32 s4, s4, 7
	s_lshl_b32 s3, s8, 10
	s_add_u32 s3, s3, 0x11583200
	v_add_u32_e32 v89, s3, v80
	v_add_u32_e32 v90, 0x1000, v89
	v_add_u32_e32 v88, 0xfffff000, v89
	v_add_u32_e32 v87, 0xffffe000, v89
	v_add_u32_e32 v91, 0x2100000, v89
	s_cmp_gt_i32 s12, -8
	s_cbranch_scc1 .Lmy_pool_l0
	s_cmp_lt_i32 s4, -8
	s_cbranch_scc1 .Lmy_pool_l0
	s_mov_b32 exec_lo, 0
	s_mov_b32 exec_hi, 0xffff0000
	global_load_dwordx4 v[0:3], v87, s[94:95]
.Lmy_pool_l0:
	s_cmp_gt_i32 s12, -7
	s_cbranch_scc1 .Lmy_pool_l1
	s_cmp_lt_i32 s4, -7
	s_cbranch_scc1 .Lmy_pool_l1
	s_mov_b32 exec_lo, 0
	s_mov_b32 exec_hi, 0xffff0000
	global_load_dwordx4 v[4:7], v87, s[94:95] offset:1024
.Lmy_pool_l1:
	s_cmp_gt_i32 s12, -6
	s_cbranch_scc1 .Lmy_pool_l2
	s_cmp_lt_i32 s4, -6
	s_cbranch_scc1 .Lmy_pool_l2
	s_mov_b32 exec_lo, 0
	s_mov_b32 exec_hi, 0xffff0000
	global_load_dwordx4 v[8:11], v87, s[94:95] offset:2048
.Lmy_pool_l2:
	s_cmp_gt_i32 s12, -5
	s_cbranch_scc1 .Lmy_pool_l3
	s_cmp_lt_i32 s4, -5
	s_cbranch_scc1 .Lmy_pool_l3
	s_mov_b32 exec_lo, 0
	s_mov_b32 exec_hi, 0xffff0000
	global_load_dwordx4 v[12:15], v87, s[94:95] offset:3072
.Lmy_pool_l3:
	s_cmp_gt_i32 s12, -4
	s_cbranch_scc1 .Lmy_pool_l4
	s_cmp_lt_i32 s4, -4
	s_cbranch_scc1 .Lmy_pool_l4
	s_mov_b32 exec_lo, 0
	s_mov_b32 exec_hi, -1
	global_load_dwordx4 v[16:19], v88, s[94:95]
.Lmy_pool_l4:
	s_cmp_gt_i32 s12, -3
	s_cbranch_scc1 .Lmy_pool_l5
	s_cmp_lt_i32 s4, -3
	s_cbranch_scc1 .Lmy_pool_l5
	s_mov_b32 exec_lo, 0
	s_mov_b32 exec_hi, -1
	global_load_dwordx4 v[20:23], v88, s[94:95] offset:1024
.Lmy_pool_l5:
	s_cmp_gt_i32 s12, -2
	s_cbranch_scc1 .Lmy_pool_l6
	s_cmp_lt_i32 s4, -2
	s_cbranch_scc1 .Lmy_pool_l6
	s_mov_b32 exec_lo, 0xffff0000
	s_mov_b32 exec_hi, -1
	global_load_dwordx4 v[24:27], v88, s[94:95] offset:2048
.Lmy_pool_l6:
	s_cmp_gt_i32 s12, -1
	s_cbranch_scc1 .Lmy_pool_l7
	s_cmp_lt_i32 s4, -1
	s_cbranch_scc1 .Lmy_pool_l7
	s_mov_b32 exec_lo, -1
	s_mov_b32 exec_hi, -1
	global_load_dwordx4 v[28:31], v88, s[94:95] offset:3072
.Lmy_pool_l7:
	s_cmp_gt_i32 s12, 0
	s_cbranch_scc1 .Lmy_pool_l8
	s_cmp_lt_i32 s4, 0
	s_cbranch_scc1 .Lmy_pool_l8
	s_mov_b32 exec_lo, -1
	s_mov_b32 exec_hi, -1
	global_load_dwordx4 v[32:35], v89, s[94:95]
.Lmy_pool_l8:
	s_cmp_gt_i32 s12, 1
	s_cbranch_scc1 .Lmy_pool_l9
	s_cmp_lt_i32 s4, 1
	s_cbranch_scc1 .Lmy_pool_l9
	s_mov_b32 exec_lo, 0xffff0000
	s_mov_b32 exec_hi, -1
	global_load_dwordx4 v[36:39], v89, s[94:95] offset:1024
.Lmy_pool_l9:
	s_cmp_gt_i32 s12, 2
	s_cbranch_scc1 .Lmy_pool_l10
	s_cmp_lt_i32 s4, 2
	s_cbranch_scc1 .Lmy_pool_l10
	s_mov_b32 exec_lo, 0
	s_mov_b32 exec_hi, -1
	global_load_dwordx4 v[40:43], v89, s[94:95] offset:2048
.Lmy_pool_l10:
	s_cmp_gt_i32 s12, 3
	s_cbranch_scc1 .Lmy_pool_l11
	s_cmp_lt_i32 s4, 3
	s_cbranch_scc1 .Lmy_pool_l11
	s_mov_b32 exec_lo, 0
	s_mov_b32 exec_hi, -1
	global_load_dwordx4 v[44:47], v89, s[94:95] offset:3072
.Lmy_pool_l11:
	s_cmp_gt_i32 s12, 4
	s_cbranch_scc1 .Lmy_pool_l12
	s_cmp_lt_i32 s4, 4
	s_cbranch_scc1 .Lmy_pool_l12
	s_mov_b32 exec_lo, 0
	s_mov_b32 exec_hi, 0xffff0000
	global_load_dwordx4 v[48:51], v90, s[94:95]
.Lmy_pool_l12:
	s_cmp_gt_i32 s12, 5
	s_cbranch_scc1 .Lmy_pool_l13
	s_cmp_lt_i32 s4, 5
	s_cbranch_scc1 .Lmy_pool_l13
	s_mov_b32 exec_lo, 0
	s_mov_b32 exec_hi, 0xffff0000
	global_load_dwordx4 v[52:55], v90, s[94:95] offset:1024
.Lmy_pool_l13:
	s_cmp_gt_i32 s12, 6
	s_cbranch_scc1 .Lmy_pool_l14
	s_cmp_lt_i32 s4, 6
	s_cbranch_scc1 .Lmy_pool_l14
	s_mov_b32 exec_lo, 0
	s_mov_b32 exec_hi, 0xffff0000
	global_load_dwordx4 v[56:59], v90, s[94:95] offset:2048
.Lmy_pool_l14:
	s_cmp_gt_i32 s12, 7
	s_cbranch_scc1 .Lmy_pool_l15
	s_cmp_lt_i32 s4, 7
	s_cbranch_scc1 .Lmy_pool_l15
	s_mov_b32 exec_lo, 0
	s_mov_b32 exec_hi, 0xffff0000
	global_load_dwordx4 v[60:63], v90, s[94:95] offset:3072
.Lmy_pool_l15:
	s_mov_b64 exec, -1
	v_sub_u32_e32 v85, s10, v81
	v_max_i32_e32 v85, 0, v85
	v_add_u32_e32 v86, s10, v82
	v_add_u32_e32 v86, 1, v86
	v_min_i32_e32 v86, s11, v86
	v_sub_u32_e32 v83, v86, v85
	v_cvt_f32_i32_e32 v83, v83
	v_rcp_f32_e32 v84, v83
	v_mov_b32_e32 v64, 0
	v_mov_b32_e32 v65, 0
	v_mov_b32_e32 v66, 0
	v_mov_b32_e32 v67, 0
	v_mov_b32_e32 v68, 0
	v_mov_b32_e32 v69, 0
	v_mov_b32_e32 v70, 0
	v_mov_b32_e32 v71, 0
	v_fma_f32 v85, -v83, v84, 1.0
	v_fmac_f32_e32 v84, v85, v84
	s_waitcnt vmcnt(0)
	s_cmp_gt_i32 s12, -8
	s_cbranch_scc1 .Lmy_pool_a0
	s_cmp_lt_i32 s4, -8
	s_cbranch_scc1 .Lmy_pool_a0
	s_mov_b32 exec_lo, 0
	s_mov_b32 exec_hi, 0xffff0000
	v_lshlrev_b32_e32 v85, 16, v0
	v_and_b32_e32 v86, 0xffff0000, v0
	v_add_f32_e32 v64, v64, v85
	v_add_f32_e32 v65, v65, v86
	v_lshlrev_b32_e32 v85, 16, v1
	v_and_b32_e32 v86, 0xffff0000, v1
	v_add_f32_e32 v66, v66, v85
	v_add_f32_e32 v67, v67, v86
	v_lshlrev_b32_e32 v85, 16, v2
	v_and_b32_e32 v86, 0xffff0000, v2
	v_add_f32_e32 v68, v68, v85
	v_add_f32_e32 v69, v69, v86
	v_lshlrev_b32_e32 v85, 16, v3
	v_and_b32_e32 v86, 0xffff0000, v3
	v_add_f32_e32 v70, v70, v85
	v_add_f32_e32 v71, v71, v86
; DI float bflo(unsigned u) { return __uint_as_float(u << 16); }
; DI float bfhi(unsigned u) { return __uint_as_float(u & 0xffff0000u); }
; DI void phase_od_pool(const Params& P) {
;     ...
;     for (size_t i = gtid; i < (size_t)RT * 64; i += gstride) {
;         const int row = (int)(i >> 6), c = (int)(i & 63) * 8, grp = c >> 7;
;         const int w = 2 << grp, left = w >> 1, right = w - 1 - left;
;         int base, n, t;
;         if (row < RL) { base = row & ~8191; n = SEQ; t = row & 8191; } else { const int rc = row - RL; base = RL + (rc & ~255); n = CTX; t = rc & 255; }
;         const int lo = max(t - left, 0), hi = min(t + right + 1, n);
;         float acc[8] = {0.f, 0.f, 0.f, 0.f, 0.f, 0.f, 0.f, 0.f};
; #pragma unroll 4
;         for (int tt = lo; tt < hi; ++tt) {
;             const u32x4 v = *(const u32x4*)(U + (size_t)(base + tt) * 512 + c);
;             acc[0] += bflo(v.x); acc[1] += bfhi(v.x); acc[2] += bflo(v.y); acc[3] += bfhi(v.y); acc[4] += bflo(v.z); acc[5] += bfhi(v.z); acc[6] += bflo(v.w); acc[7] += bfhi(v.w);
;         }
.Lmy_pool_a0:
	s_cmp_gt_i32 s12, -7
	s_cbranch_scc1 .Lmy_pool_a1
	s_cmp_lt_i32 s4, -7
	s_cbranch_scc1 .Lmy_pool_a1
	s_mov_b32 exec_lo, 0
	s_mov_b32 exec_hi, 0xffff0000
	v_lshlrev_b32_e32 v85, 16, v4
	v_and_b32_e32 v86, 0xffff0000, v4
	v_add_f32_e32 v64, v64, v85
	v_add_f32_e32 v65, v65, v86
	v_lshlrev_b32_e32 v85, 16, v5
	v_and_b32_e32 v86, 0xffff0000, v5
	v_add_f32_e32 v66, v66, v85
	v_add_f32_e32 v67, v67, v86
	v_lshlrev_b32_e32 v85, 16, v6
	v_and_b32_e32 v86, 0xffff0000, v6
	v_add_f32_e32 v68, v68, v85
	v_add_f32_e32 v69, v69, v86
	v_lshlrev_b32_e32 v85, 16, v7
	v_and_b32_e32 v86, 0xffff0000, v7
	v_add_f32_e32 v70, v70, v85
	v_add_f32_e32 v71, v71, v86
.Lmy_pool_a1:
	s_cmp_gt_i32 s12, -6
	s_cbranch_scc1 .Lmy_pool_a2
	s_cmp_lt_i32 s4, -6
	s_cbranch_scc1 .Lmy_pool_a2
	s_mov_b32 exec_lo, 0
	s_mov_b32 exec_hi, 0xffff0000
	v_lshlrev_b32_e32 v85, 16, v8
	v_and_b32_e32 v86, 0xffff0000, v8
	v_add_f32_e32 v64, v64, v85
	v_add_f32_e32 v65, v65, v86
	v_lshlrev_b32_e32 v85, 16, v9
	v_and_b32_e32 v86, 0xffff0000, v9
	v_add_f32_e32 v66, v66, v85
	v_add_f32_e32 v67, v67, v86
	v_lshlrev_b32_e32 v85, 16, v10
	v_and_b32_e32 v86, 0xffff0000, v10
	v_add_f32_e32 v68, v68, v85
	v_add_f32_e32 v69, v69, v86
	v_lshlrev_b32_e32 v85, 16, v11
	v_and_b32_e32 v86, 0xffff0000, v11
	v_add_f32_e32 v70, v70, v85
	v_add_f32_e32 v71, v71, v86
.Lmy_pool_a2:
	s_cmp_gt_i32 s12, -5
	s_cbranch_scc1 .Lmy_pool_a3
	s_cmp_lt_i32 s4, -5
	s_cbranch_scc1 .Lmy_pool_a3
	s_mov_b32 exec_lo, 0
	s_mov_b32 exec_hi, 0xffff0000
	v_lshlrev_b32_e32 v85, 16, v12
	v_and_b32_e32 v86, 0xffff0000, v12
	v_add_f32_e32 v64, v64, v85
	v_add_f32_e32 v65, v65, v86
	v_lshlrev_b32_e32 v85, 16, v13
	v_and_b32_e32 v86, 0xffff0000, v13
	v_add_f32_e32 v66, v66, v85
	v_add_f32_e32 v67, v67, v86
	v_lshlrev_b32_e32 v85, 16, v14
	v_and_b32_e32 v86, 0xffff0000, v14
	v_add_f32_e32 v68, v68, v85
	v_add_f32_e32 v69, v69, v86
	v_lshlrev_b32_e32 v85, 16, v15
	v_and_b32_e32 v86, 0xffff0000, v15
	v_add_f32_e32 v70, v70, v85
	v_add_f32_e32 v71, v71, v86
.Lmy_pool_a3:
	s_cmp_gt_i32 s12, -4
	s_cbranch_scc1 .Lmy_pool_a4
	s_cmp_lt_i32 s4, -4
	s_cbranch_scc1 .Lmy_pool_a4
	s_mov_b32 exec_lo, 0
	s_mov_b32 exec_hi, -1
	v_lshlrev_b32_e32 v85, 16, v16
	v_and_b32_e32 v86, 0xffff0000, v16
	v_add_f32_e32 v64, v64, v85
	v_add_f32_e32 v65, v65, v86
	v_lshlrev_b32_e32 v85, 16, v17
	v_and_b32_e32 v86, 0xffff0000, v17
	v_add_f32_e32 v66, v66, v85
	v_add_f32_e32 v67, v67, v86
	v_lshlrev_b32_e32 v85, 16, v18
	v_and_b32_e32 v86, 0xffff0000, v18
	v_add_f32_e32 v68, v68, v85
	v_add_f32_e32 v69, v69, v86
	v_lshlrev_b32_e32 v85, 16, v19
	v_and_b32_e32 v86, 0xffff0000, v19
	v_add_f32_e32 v70, v70, v85
	v_add_f32_e32 v71, v71, v86
.Lmy_pool_a4:
	s_cmp_gt_i32 s12, -3
	s_cbranch_scc1 .Lmy_pool_a5
	s_cmp_lt_i32 s4, -3
	s_cbranch_scc1 .Lmy_pool_a5
	s_mov_b32 exec_lo, 0
	s_mov_b32 exec_hi, -1
	v_lshlrev_b32_e32 v85, 16, v20
	v_and_b32_e32 v86, 0xffff0000, v20
	v_add_f32_e32 v64, v64, v85
	v_add_f32_e32 v65, v65, v86
	v_lshlrev_b32_e32 v85, 16, v21
	v_and_b32_e32 v86, 0xffff0000, v21
	v_add_f32_e32 v66, v66, v85
	v_add_f32_e32 v67, v67, v86
	v_lshlrev_b32_e32 v85, 16, v22
	v_and_b32_e32 v86, 0xffff0000, v22
	v_add_f32_e32 v68, v68, v85
	v_add_f32_e32 v69, v69, v86
	v_lshlrev_b32_e32 v85, 16, v23
	v_and_b32_e32 v86, 0xffff0000, v23
	v_add_f32_e32 v70, v70, v85
	v_add_f32_e32 v71, v71, v86
.Lmy_pool_a5:
	s_cmp_gt_i32 s12, -2
	s_cbranch_scc1 .Lmy_pool_a6
	s_cmp_lt_i32 s4, -2
	s_cbranch_scc1 .Lmy_pool_a6
	s_mov_b32 exec_lo, 0xffff0000
	s_mov_b32 exec_hi, -1
	v_lshlrev_b32_e32 v85, 16, v24
	v_and_b32_e32 v86, 0xffff0000, v24
	v_add_f32_e32 v64, v64, v85
	v_add_f32_e32 v65, v65, v86
	v_lshlrev_b32_e32 v85, 16, v25
	v_and_b32_e32 v86, 0xffff0000, v25
	v_add_f32_e32 v66, v66, v85
	v_add_f32_e32 v67, v67, v86
	v_lshlrev_b32_e32 v85, 16, v26
	v_and_b32_e32 v86, 0xffff0000, v26
	v_add_f32_e32 v68, v68, v85
	v_add_f32_e32 v69, v69, v86
	v_lshlrev_b32_e32 v85, 16, v27
	v_and_b32_e32 v86, 0xffff0000, v27
	v_add_f32_e32 v70, v70, v85
	v_add_f32_e32 v71, v71, v86
.Lmy_pool_a6:
	s_cmp_gt_i32 s12, -1
	s_cbranch_scc1 .Lmy_pool_a7
	s_cmp_lt_i32 s4, -1
	s_cbranch_scc1 .Lmy_pool_a7
	s_mov_b32 exec_lo, -1
	s_mov_b32 exec_hi, -1
	v_lshlrev_b32_e32 v85, 16, v28
	v_and_b32_e32 v86, 0xffff0000, v28
	v_add_f32_e32 v64, v64, v85
	v_add_f32_e32 v65, v65, v86
	v_lshlrev_b32_e32 v85, 16, v29
	v_and_b32_e32 v86, 0xffff0000, v29
	v_add_f32_e32 v66, v66, v85
	v_add_f32_e32 v67, v67, v86
	v_lshlrev_b32_e32 v85, 16, v30
	v_and_b32_e32 v86, 0xffff0000, v30
	v_add_f32_e32 v68, v68, v85
	v_add_f32_e32 v69, v69, v86
	v_lshlrev_b32_e32 v85, 16, v31
	v_and_b32_e32 v86, 0xffff0000, v31
	v_add_f32_e32 v70, v70, v85
	v_add_f32_e32 v71, v71, v86
.Lmy_pool_a7:
	s_cmp_gt_i32 s12, 0
	s_cbranch_scc1 .Lmy_pool_a8
	s_cmp_lt_i32 s4, 0
	s_cbranch_scc1 .Lmy_pool_a8
	s_mov_b32 exec_lo, -1
	s_mov_b32 exec_hi, -1
	v_lshlrev_b32_e32 v72, 16, v32
	v_and_b32_e32 v73, 0xffff0000, v32
	v_add_f32_e32 v64, v64, v72
	v_add_f32_e32 v65, v65, v73
	v_lshlrev_b32_e32 v74, 16, v33
	v_and_b32_e32 v75, 0xffff0000, v33
	v_add_f32_e32 v66, v66, v74
	v_add_f32_e32 v67, v67, v75
	v_lshlrev_b32_e32 v76, 16, v34
	v_and_b32_e32 v77, 0xffff0000, v34
	v_add_f32_e32 v68, v68, v76
	v_add_f32_e32 v69, v69, v77
	v_lshlrev_b32_e32 v78, 16, v35
	v_and_b32_e32 v79, 0xffff0000, v35
	v_add_f32_e32 v70, v70, v78
	v_add_f32_e32 v71, v71, v79
; DI unsigned pk2(float a, float b) { f32x2 v = {a, b}; bfx2 r = __builtin_convertvector(v, bfx2); return __builtin_bit_cast(unsigned, r); }
; DI float bflo(unsigned u) { return __uint_as_float(u << 16); }
; DI float bfhi(unsigned u) { return __uint_as_float(u & 0xffff0000u); }
; DI void phase_od_pool(const Params& P) {
;     ...
;     for (size_t i = gtid; i < (size_t)RT * 64; i += gstride) {
;         const int row = (int)(i >> 6), c = (int)(i & 63) * 8, grp = c >> 7;
;         const int w = 2 << grp, left = w >> 1, right = w - 1 - left;
;         int base, n, t;
;         if (row < RL) { base = row & ~8191; n = SEQ; t = row & 8191; } else { const int rc = row - RL; base = RL + (rc & ~255); n = CTX; t = rc & 255; }
;         const int lo = max(t - left, 0), hi = min(t + right + 1, n);
;         float acc[8] = {0.f, 0.f, 0.f, 0.f, 0.f, 0.f, 0.f, 0.f};
; #pragma unroll 4
;         for (int tt = lo; tt < hi; ++tt) {
;             const u32x4 v = *(const u32x4*)(U + (size_t)(base + tt) * 512 + c);
;             acc[0] += bflo(v.x); acc[1] += bfhi(v.x); acc[2] += bflo(v.y); acc[3] += bfhi(v.y); acc[4] += bflo(v.z); acc[5] += bfhi(v.z); acc[6] += bflo(v.w); acc[7] += bfhi(v.w);
;         }
;         const float ic = 1.f / (float)(hi - lo);
;         const u32x4 s = *(const u32x4*)(U + (size_t)row * 512 + c);
;         u32x4 o;
;         o.x = pk2(acc[0] * ic - bflo(s.x), acc[1] * ic - bfhi(s.x)); o.y = pk2(acc[2] * ic - bflo(s.y), acc[3] * ic - bfhi(s.y));
;         o.z = pk2(acc[4] * ic - bflo(s.z), acc[5] * ic - bfhi(s.z)); o.w = pk2(acc[6] * ic - bflo(s.w), acc[7] * ic - bfhi(s.w));
;         *(u32x4*)(PL + (size_t)row * 512 + c) = o;
;     }
.Lmy_pool_a8:
	s_cmp_gt_i32 s12, 1
	s_cbranch_scc1 .Lmy_pool_a9
	s_cmp_lt_i32 s4, 1
	s_cbranch_scc1 .Lmy_pool_a9
	s_mov_b32 exec_lo, 0xffff0000
	s_mov_b32 exec_hi, -1
	v_lshlrev_b32_e32 v85, 16, v36
	v_and_b32_e32 v86, 0xffff0000, v36
	v_add_f32_e32 v64, v64, v85
	v_add_f32_e32 v65, v65, v86
	v_lshlrev_b32_e32 v85, 16, v37
	v_and_b32_e32 v86, 0xffff0000, v37
	v_add_f32_e32 v66, v66, v85
	v_add_f32_e32 v67, v67, v86
	v_lshlrev_b32_e32 v85, 16, v38
	v_and_b32_e32 v86, 0xffff0000, v38
	v_add_f32_e32 v68, v68, v85
	v_add_f32_e32 v69, v69, v86
	v_lshlrev_b32_e32 v85, 16, v39
	v_and_b32_e32 v86, 0xffff0000, v39
	v_add_f32_e32 v70, v70, v85
	v_add_f32_e32 v71, v71, v86
.Lmy_pool_a9:
	s_cmp_gt_i32 s12, 2
	s_cbranch_scc1 .Lmy_pool_a10
	s_cmp_lt_i32 s4, 2
	s_cbranch_scc1 .Lmy_pool_a10
	s_mov_b32 exec_lo, 0
	s_mov_b32 exec_hi, -1
	v_lshlrev_b32_e32 v85, 16, v40
	v_and_b32_e32 v86, 0xffff0000, v40
	v_add_f32_e32 v64, v64, v85
	v_add_f32_e32 v65, v65, v86
	v_lshlrev_b32_e32 v85, 16, v41
	v_and_b32_e32 v86, 0xffff0000, v41
	v_add_f32_e32 v66, v66, v85
	v_add_f32_e32 v67, v67, v86
	v_lshlrev_b32_e32 v85, 16, v42
	v_and_b32_e32 v86, 0xffff0000, v42
	v_add_f32_e32 v68, v68, v85
	v_add_f32_e32 v69, v69, v86
	v_lshlrev_b32_e32 v85, 16, v43
	v_and_b32_e32 v86, 0xffff0000, v43
	v_add_f32_e32 v70, v70, v85
	v_add_f32_e32 v71, v71, v86
.Lmy_pool_a10:
	s_cmp_gt_i32 s12, 3
	s_cbranch_scc1 .Lmy_pool_a11
	s_cmp_lt_i32 s4, 3
	s_cbranch_scc1 .Lmy_pool_a11
	s_mov_b32 exec_lo, 0
	s_mov_b32 exec_hi, -1
	v_lshlrev_b32_e32 v85, 16, v44
	v_and_b32_e32 v86, 0xffff0000, v44
	v_add_f32_e32 v64, v64, v85
	v_add_f32_e32 v65, v65, v86
	v_lshlrev_b32_e32 v85, 16, v45
	v_and_b32_e32 v86, 0xffff0000, v45
	v_add_f32_e32 v66, v66, v85
	v_add_f32_e32 v67, v67, v86
	v_lshlrev_b32_e32 v85, 16, v46
	v_and_b32_e32 v86, 0xffff0000, v46
	v_add_f32_e32 v68, v68, v85
	v_add_f32_e32 v69, v69, v86
	v_lshlrev_b32_e32 v85, 16, v47
	v_and_b32_e32 v86, 0xffff0000, v47
	v_add_f32_e32 v70, v70, v85
	v_add_f32_e32 v71, v71, v86
.Lmy_pool_a11:
	s_cmp_gt_i32 s12, 4
	s_cbranch_scc1 .Lmy_pool_a12
	s_cmp_lt_i32 s4, 4
	s_cbranch_scc1 .Lmy_pool_a12
	s_mov_b32 exec_lo, 0
	s_mov_b32 exec_hi, 0xffff0000
	v_lshlrev_b32_e32 v85, 16, v48
	v_and_b32_e32 v86, 0xffff0000, v48
	v_add_f32_e32 v64, v64, v85
	v_add_f32_e32 v65, v65, v86
	v_lshlrev_b32_e32 v85, 16, v49
	v_and_b32_e32 v86, 0xffff0000, v49
	v_add_f32_e32 v66, v66, v85
	v_add_f32_e32 v67, v67, v86
	v_lshlrev_b32_e32 v85, 16, v50
	v_and_b32_e32 v86, 0xffff0000, v50
	v_add_f32_e32 v68, v68, v85
	v_add_f32_e32 v69, v69, v86
	v_lshlrev_b32_e32 v85, 16, v51
	v_and_b32_e32 v86, 0xffff0000, v51
	v_add_f32_e32 v70, v70, v85
	v_add_f32_e32 v71, v71, v86
.Lmy_pool_a12:
	s_cmp_gt_i32 s12, 5
	s_cbranch_scc1 .Lmy_pool_a13
	s_cmp_lt_i32 s4, 5
	s_cbranch_scc1 .Lmy_pool_a13
	s_mov_b32 exec_lo, 0
	s_mov_b32 exec_hi, 0xffff0000
	v_lshlrev_b32_e32 v85, 16, v52
	v_and_b32_e32 v86, 0xffff0000, v52
	v_add_f32_e32 v64, v64, v85
	v_add_f32_e32 v65, v65, v86
	v_lshlrev_b32_e32 v85, 16, v53
	v_and_b32_e32 v86, 0xffff0000, v53
	v_add_f32_e32 v66, v66, v85
	v_add_f32_e32 v67, v67, v86
	v_lshlrev_b32_e32 v85, 16, v54
	v_and_b32_e32 v86, 0xffff0000, v54
	v_add_f32_e32 v68, v68, v85
	v_add_f32_e32 v69, v69, v86
	v_lshlrev_b32_e32 v85, 16, v55
	v_and_b32_e32 v86, 0xffff0000, v55
	v_add_f32_e32 v70, v70, v85
	v_add_f32_e32 v71, v71, v86
.Lmy_pool_a13:
	s_cmp_gt_i32 s12, 6
	s_cbranch_scc1 .Lmy_pool_a14
	s_cmp_lt_i32 s4, 6
	s_cbranch_scc1 .Lmy_pool_a14
	s_mov_b32 exec_lo, 0
	s_mov_b32 exec_hi, 0xffff0000
	v_lshlrev_b32_e32 v85, 16, v56
	v_and_b32_e32 v86, 0xffff0000, v56
	v_add_f32_e32 v64, v64, v85
	v_add_f32_e32 v65, v65, v86
	v_lshlrev_b32_e32 v85, 16, v57
	v_and_b32_e32 v86, 0xffff0000, v57
	v_add_f32_e32 v66, v66, v85
	v_add_f32_e32 v67, v67, v86
	v_lshlrev_b32_e32 v85, 16, v58
	v_and_b32_e32 v86, 0xffff0000, v58
	v_add_f32_e32 v68, v68, v85
	v_add_f32_e32 v69, v69, v86
	v_lshlrev_b32_e32 v85, 16, v59
	v_and_b32_e32 v86, 0xffff0000, v59
	v_add_f32_e32 v70, v70, v85
	v_add_f32_e32 v71, v71, v86
.Lmy_pool_a14:
	s_cmp_gt_i32 s12, 7
	s_cbranch_scc1 .Lmy_pool_a15
	s_cmp_lt_i32 s4, 7
	s_cbranch_scc1 .Lmy_pool_a15
	s_mov_b32 exec_lo, 0
	s_mov_b32 exec_hi, 0xffff0000
	v_lshlrev_b32_e32 v85, 16, v60
	v_and_b32_e32 v86, 0xffff0000, v60
	v_add_f32_e32 v64, v64, v85
	v_add_f32_e32 v65, v65, v86
	v_lshlrev_b32_e32 v85, 16, v61
	v_and_b32_e32 v86, 0xffff0000, v61
	v_add_f32_e32 v66, v66, v85
	v_add_f32_e32 v67, v67, v86
	v_lshlrev_b32_e32 v85, 16, v62
	v_and_b32_e32 v86, 0xffff0000, v62
	v_add_f32_e32 v68, v68, v85
	v_add_f32_e32 v69, v69, v86
	v_lshlrev_b32_e32 v85, 16, v63
	v_and_b32_e32 v86, 0xffff0000, v63
	v_add_f32_e32 v70, v70, v85
	v_add_f32_e32 v71, v71, v86
.Lmy_pool_a15:
	s_mov_b64 exec, -1
	v_fma_f32 v64, v64, v84, -v72
	v_fma_f32 v65, v65, v84, -v73
	v_fma_f32 v66, v66, v84, -v74
	v_fma_f32 v67, v67, v84, -v75
	v_fma_f32 v68, v68, v84, -v76
	v_fma_f32 v69, v69, v84, -v77
	v_fma_f32 v70, v70, v84, -v78
	v_fma_f32 v71, v71, v84, -v79
	v_cvt_pk_bf16_f32 v92, v64, v65
	v_cvt_pk_bf16_f32 v93, v66, v67
	v_cvt_pk_bf16_f32 v94, v68, v69
	v_cvt_pk_bf16_f32 v95, v70, v71
	global_store_dwordx4 v91, v[92:95], s[94:95]
	s_add_u32 s8, s8, s9
	s_cmp_lt_u32 s8, 0x8400
	s_cbranch_scc1 .Lmy_pool_loop
.Lmy_pool_done:
	s_branch .LBB0_537
	v_readlane_b32 s0, v253, 0
	s_mov_b32 s2, s0
	s_ashr_i32 s3, s2, 31
	v_mov_b32_e32 v2, v194
	s_lshl_b64 s[0:1], s[2:3], 9
	s_nop 0
	v_ashrrev_i32_e32 v3, 31, v2
	v_lshl_add_u64 v[0:1], s[0:1], 0, v[2:3]
	s_mov_b64 s[0:1], 0x210000
	v_cmp_gt_u64_e32 vcc, s[0:1], v[0:1]
	s_and_saveexec_b64 s[0:1], vcc
	s_cbranch_execz .LBB0_537
	v_readlane_b32 s4, v253, 9
	v_readlane_b32 s5, v253, 10
	v_readlane_b32 s6, v254, 53
	s_load_dword s8, s[4:5], 0x0
	v_readlane_b32 s7, v254, 54
	s_mov_b32 s9, s7
	v_lshlrev_b32_e32 v2, 3, v2
	s_mov_b32 s3, s9
	v_lshl_add_u32 v18, s2, 12, v2
	v_writelane_b32 v254, s2, 53
	s_waitcnt lgkmcnt(0)
	s_lshl_b64 s[6:7], s[8:9], 9
	s_lshl_b32 s12, s8, 12
	v_writelane_b32 v254, s3, 54
	s_mov_b64 s[8:9], 0
	s_branch .LBB0_526

; DI void grid_barrier(unsigned* ctr, unsigned target) {
;     __syncthreads();
;     if (threadIdx.x == 0) {
;         __builtin_amdgcn_fence(__ATOMIC_RELEASE, "agent");
;         __hip_atomic_fetch_add(ctr, 1u, __ATOMIC_RELAXED, __HIP_MEMORY_SCOPE_AGENT);
;         while (__hip_atomic_load(ctr, __ATOMIC_RELAXED, __HIP_MEMORY_SCOPE_AGENT) < target) __builtin_amdgcn_s_sleep(2);
;         __builtin_amdgcn_fence(__ATOMIC_ACQUIRE, "agent");
;     }
;     __syncthreads();
; }
; __global__ void __launch_bounds__(NTHR, 2) mega(Params P, int ph_lo, int ph_hi) {
;     ...
;         if (ph + 1 < ph_hi) {
;             if (ph == ph_lo) cg::this_grid().sync();
;             else { ++nsync; grid_barrier((unsigned*)(P.ws + OFF_BAR), nsync * gridDim.x); }
.LBB0_1728:
	v_readlane_b32 s0, v253, 1
	v_readlane_b32 s1, v253, 2
	s_cmp_lg_u32 s2, s0
	s_mov_b64 s[0:1], -1
	v_readlane_b32 s0, v254, 52
	s_add_i32 s6, s0, 1
	s_waitcnt vmcnt(63) expcnt(7) lgkmcnt(15)
	s_barrier
	s_mov_b64 s[0:1], exec
	v_readlane_b32 s2, v254, 55
	v_readlane_b32 s3, v254, 56
	s_and_b64 s[2:3], s[0:1], s[2:3]
	s_mov_b64 exec, s[2:3]
	s_cbranch_execz .LBB0_1735
	s_mov_b64 s[2:3], exec
	v_mbcnt_lo_u32_b32 v0, s2, 0
	v_mbcnt_hi_u32_b32 v0, s3, v0
	v_cmp_eq_u32_e32 vcc, 0, v0
	buffer_wbl2 sc1
	s_waitcnt vmcnt(0)
	s_and_saveexec_b64 s[4:5], vcc
	v_readlane_b32 s12, v254, 47
	v_readlane_b32 s13, v254, 48
	s_cbranch_execz .LBB0_1732
	s_bcnt1_i32_b64 s2, s[2:3]
	v_mov_b32_e32 v0, s2
	s_nop 1
	global_atomic_add v173, v0, s[12:13]
